# native-layout unit epilogue plus gate rows prefetched by LDS-DMA into the idle stage during the last tile
# speedup vs baseline: 1.0042x; 1.0042x over previous
.Lat_entry:
	s_mov_b32 s92, m0
	s_add_i32 s71, s97, 0x10000
	s_mov_b32 s70, 0
	s_movk_i32 s81, 0x7f
	s_mov_b32 s80, 0x20000
	s_add_i32 s51, s90, 0x80000
	s_add_u32 s50, s62, s51
	s_addc_u32 s51, s63, 0
	s_mov_b32 s84, 1
	s_mov_b32 s94, 0xff800000
	v_mov_b32_e32 v246, 0
	v_mov_b32_e32 v247, 0
	v_mov_b32_e32 v248, 0
	v_mov_b32_e32 v249, 0
	v_mov_b32_e32 v250, 0
	v_mov_b32_e32 v251, 0
	v_mov_b32_e32 v252, 0
	v_mov_b32_e32 v253, 0
	v_readlane_b32 s4, v254, 24
	v_and_b32_e32 v234, 15, v211
	v_lshrrev_b32_e32 v235, 4, v211
	v_xor_b32_e32 v236, v234, v235
	v_lshlrev_b32_e32 v236, 4, v236
	v_lshl_add_u32 v236, v234, 8, v236
	v_add_u32_e32 v221, s4, v236
	v_lshlrev_b32_e32 v237, 2, v235
	v_sub_u32_e32 v237, v234, v237
	v_add_u32_e32 v223, s3, v237
	v_bfe_u32 v237, v211, 5, 1
	v_lshlrev_b32_e32 v237, 12, v237
	v_bfe_u32 v238, v211, 4, 1
	v_lshl_add_u32 v237, v238, 7, v237
	v_bfe_u32 v238, v211, 2, 2
	v_lshl_add_u32 v237, v238, 5, v237
	v_and_b32_e32 v238, 3, v211
	v_lshl_add_u32 v237, v238, 3, v237
	v_add_u32_e32 v222, 0x8000, v237
	v_mov_b32_e32 v243, v233
	v_mov_b32_e32 v244, 0
	v_xor_b32_e32 v234, s70, v221
	v_xor_b32_e32 v235, 64, v234
	v_xor_b32_e32 v236, 0x80, v234
	v_xor_b32_e32 v237, 0xc0, v234
	s_lshl_b64 s[98:99], s[82:83], 1
	s_add_u32 s98, s48, s98
	s_addc_u32 s99, s49, s99
	v_readlane_b32 s4, v254, 27
	s_nop 1
	v_add_u32_e32 v245, s4, v218
	v_add_u32_e32 v245, s3, v245
	v_lshlrev_b32_e32 v245, 13, v245
	v_lshl_add_u32 v245, v217, 4, v245

.Lat_end_a:
.Lat_next:
	s_add_i32 s58, s58, 1
	s_xor_b32 s70, s70, 0x10000
	s_xor_b32 s71, s71, 0x10000
	v_add_u32_e32 v223, 0xffffffc0, v223
	s_addk_i32 s91, 0x40
	s_add_u32 s50, s50, 0x80000
	s_addc_u32 s51, s51, 0
	s_mov_b32 s94, 0
	s_cmp_le_u32 s58, s88
	s_cbranch_scc1 .Lat_loop
	s_waitcnt vmcnt(0) lgkmcnt(0)
	s_barrier
	s_add_i32 m0, s71, 0x0
	s_nop 0
	global_load_lds_dwordx4 v245, s[98:99]
	s_add_i32 m0, s71, 0x400
	v_add_u32_e32 v245, 0x4000, v245
	global_load_lds_dwordx4 v245, s[98:99]
	s_add_i32 m0, s71, 0x800
	v_add_u32_e32 v245, 0x4000, v245
	global_load_lds_dwordx4 v245, s[98:99]
	s_add_i32 m0, s71, 0xc00
	v_add_u32_e32 v245, 0x4000, v245
	global_load_lds_dwordx4 v245, s[98:99]
	s_add_i32 m0, s71, 0x1000
	v_add_u32_e32 v245, 0x4000, v245
	global_load_lds_dwordx4 v245, s[98:99]
	s_add_i32 m0, s71, 0x1400
	v_add_u32_e32 v245, 0x4000, v245
	global_load_lds_dwordx4 v245, s[98:99]
	s_add_i32 m0, s71, 0x1800
	v_add_u32_e32 v245, 0x4000, v245
	global_load_lds_dwordx4 v245, s[98:99]
	s_add_i32 m0, s71, 0x1c00
	v_add_u32_e32 v245, 0x4000, v245
	global_load_lds_dwordx4 v245, s[98:99]
	s_cmp_gt_u32 s58, s89
	s_cbranch_scc1 .Lat_done
	ds_read_b128 v[162:165], v234
	ds_read_b128 v[166:169], v235
	ds_read_b128 v[170:173], v236
	ds_read_b128 v[174:177], v237
	v_add_u32_e32 v242, s70, v222
	s_waitcnt lgkmcnt(2)
	v_mfma_f32_16x16x32_bf16 v[130:133], v[162:165], v[178:181], v[246:249]
	v_mfma_f32_16x16x32_bf16 v[146:149], v[162:165], v[194:197], v[250:253]
	ds_read_b128 v[162:165], v234 offset:4096
	v_mfma_f32_16x16x32_bf16 v[130:133], v[166:169], v[182:185], v[130:133]
	v_mfma_f32_16x16x32_bf16 v[146:149], v[166:169], v[198:201], v[146:149]
	ds_read_b128 v[166:169], v235 offset:4096
	s_waitcnt lgkmcnt(2)
	v_mfma_f32_16x16x32_bf16 v[130:133], v[170:173], v[186:189], v[130:133]
	v_mfma_f32_16x16x32_bf16 v[146:149], v[170:173], v[202:205], v[146:149]
	ds_read_b128 v[170:173], v236 offset:4096
	v_mfma_f32_16x16x32_bf16 v[130:133], v[174:177], v[190:193], v[130:133]
	v_mfma_f32_16x16x32_bf16 v[146:149], v[174:177], v[206:209], v[146:149]
	ds_read_b128 v[174:177], v237 offset:4096
	s_waitcnt lgkmcnt(2)
	v_mfma_f32_16x16x32_bf16 v[134:137], v[162:165], v[178:181], v[246:249]
	v_mfma_f32_16x16x32_bf16 v[150:153], v[162:165], v[194:197], v[250:253]
	ds_read_b128 v[162:165], v234 offset:8192
	v_mfma_f32_16x16x32_bf16 v[134:137], v[166:169], v[182:185], v[134:137]
	v_mfma_f32_16x16x32_bf16 v[150:153], v[166:169], v[198:201], v[150:153]
	ds_read_b128 v[166:169], v235 offset:8192
	s_waitcnt lgkmcnt(2)
	v_mfma_f32_16x16x32_bf16 v[134:137], v[170:173], v[186:189], v[134:137]
	v_mfma_f32_16x16x32_bf16 v[150:153], v[170:173], v[202:205], v[150:153]
	ds_read_b128 v[170:173], v236 offset:8192
	v_mfma_f32_16x16x32_bf16 v[134:137], v[174:177], v[190:193], v[134:137]
	v_mfma_f32_16x16x32_bf16 v[150:153], v[174:177], v[206:209], v[150:153]
	ds_read_b128 v[174:177], v237 offset:8192
	s_waitcnt lgkmcnt(2)
	v_mfma_f32_16x16x32_bf16 v[138:141], v[162:165], v[178:181], v[246:249]
	v_mfma_f32_16x16x32_bf16 v[154:157], v[162:165], v[194:197], v[250:253]
	ds_read_b128 v[162:165], v234 offset:12288
	v_mfma_f32_16x16x32_bf16 v[138:141], v[166:169], v[182:185], v[138:141]
	v_mfma_f32_16x16x32_bf16 v[154:157], v[166:169], v[198:201], v[154:157]
	ds_read_b128 v[166:169], v235 offset:12288
	s_waitcnt lgkmcnt(2)
	v_mfma_f32_16x16x32_bf16 v[138:141], v[170:173], v[186:189], v[138:141]
	v_mfma_f32_16x16x32_bf16 v[154:157], v[170:173], v[202:205], v[154:157]
	ds_read_b128 v[170:173], v236 offset:12288
	v_mfma_f32_16x16x32_bf16 v[138:141], v[174:177], v[190:193], v[138:141]
	v_mfma_f32_16x16x32_bf16 v[154:157], v[174:177], v[206:209], v[154:157]
	ds_read_b128 v[174:177], v237 offset:12288
	s_waitcnt lgkmcnt(2)
	v_mfma_f32_16x16x32_bf16 v[142:145], v[162:165], v[178:181], v[246:249]
	v_mfma_f32_16x16x32_bf16 v[158:161], v[162:165], v[194:197], v[250:253]
	ds_read_b64_tr_b16 v[162:163], v242 offset:0
	ds_read_b64_tr_b16 v[164:165], v242 offset:8192
	v_mfma_f32_16x16x32_bf16 v[142:145], v[166:169], v[182:185], v[142:145]
	v_mfma_f32_16x16x32_bf16 v[158:161], v[166:169], v[198:201], v[158:161]
	ds_read_b64_tr_b16 v[166:167], v242 offset:16384
	ds_read_b64_tr_b16 v[168:169], v242 offset:24576
	s_waitcnt lgkmcnt(4)
	v_mfma_f32_16x16x32_bf16 v[142:145], v[170:173], v[186:189], v[142:145]
	v_mfma_f32_16x16x32_bf16 v[158:161], v[170:173], v[202:205], v[158:161]
	ds_read_b64_tr_b16 v[170:171], v242 offset:256
	ds_read_b64_tr_b16 v[172:173], v242 offset:8448
	v_mfma_f32_16x16x32_bf16 v[142:145], v[174:177], v[190:193], v[142:145]
	v_mfma_f32_16x16x32_bf16 v[158:161], v[174:177], v[206:209], v[158:161]
	ds_read_b64_tr_b16 v[174:175], v242 offset:16640
	ds_read_b64_tr_b16 v[176:177], v242 offset:24832

.Lat_end_b:
.Lat_done:
	s_waitcnt vmcnt(0) lgkmcnt(0)
	v_lshl_add_u32 v250, v211, 4, s71
	ds_read_b128 v[130:133], v250
	ds_read_b128 v[134:137], v250 offset:1024
	ds_read_b128 v[138:141], v250 offset:2048
	ds_read_b128 v[142:145], v250 offset:3072
	ds_read_b128 v[146:149], v250 offset:4096
	ds_read_b128 v[150:153], v250 offset:5120
	ds_read_b128 v[154:157], v250 offset:6144
	ds_read_b128 v[158:161], v250 offset:7168
	s_waitcnt lgkmcnt(0)
	s_barrier
	s_mov_b32 m0, s92
	s_nop 1
	v_permlane16_swap_b32_e32 v232, v244
	v_add_f32_e32 v232, v232, v244
	v_mov_b32_e32 v244, v232
	s_nop 1
	v_permlane32_swap_b32_e32 v232, v244
	v_add_f32_e32 v232, v232, v244
	v_mov_b32_e32 v244, v232
	s_nop 1
	v_permlane16_swap_b32_e32 v232, v244
	s_nop 0
	v_div_scale_f32 v162, s[6:7], v232, v232, 1.0
	v_rcp_f32_e32 v163, v162
	v_div_scale_f32 v164, vcc, 1.0, v232, 1.0
	v_fma_f32 v165, -v162, v163, 1.0
	v_fmac_f32_e32 v163, v165, v163
	v_mul_f32_e32 v165, v164, v163
	v_fma_f32 v166, -v162, v165, v164
	v_fmac_f32_e32 v165, v166, v163
	v_fma_f32 v162, -v162, v165, v164
	v_div_fmas_f32 v162, v162, v163, v165
	v_div_fixup_f32 v232, v162, v232, 1.0
	v_div_scale_f32 v167, s[6:7], v244, v244, 1.0
	v_rcp_f32_e32 v168, v167
	v_div_scale_f32 v169, vcc, 1.0, v244, 1.0
	v_fma_f32 v170, -v167, v168, 1.0
	v_fmac_f32_e32 v168, v170, v168
	v_mul_f32_e32 v170, v169, v168
	v_fma_f32 v171, -v167, v170, v169
	v_fmac_f32_e32 v170, v171, v168
	v_fma_f32 v167, -v167, v170, v169
	v_div_fmas_f32 v167, v167, v168, v170
	v_div_fixup_f32 v244, v167, v244, 1.0
	s_lshl_b64 s[4:5], s[82:83], 1
	v_mul_f32_e32 v114, v114, v232
	v_mul_f32_e32 v115, v115, v232
	v_mul_f32_e32 v116, v116, v232
	v_mul_f32_e32 v117, v117, v232
	v_mul_f32_e32 v118, v118, v232
	v_mul_f32_e32 v119, v119, v232
	v_mul_f32_e32 v120, v120, v232
	v_mul_f32_e32 v121, v121, v232
	v_mul_f32_e32 v98, v98, v232
	v_mul_f32_e32 v99, v99, v232
	v_mul_f32_e32 v100, v100, v232
	v_mul_f32_e32 v101, v101, v232
	v_mul_f32_e32 v102, v102, v232
	v_mul_f32_e32 v103, v103, v232
	v_mul_f32_e32 v104, v104, v232
	v_mul_f32_e32 v105, v105, v232
	v_mul_f32_e32 v82, v82, v232
	v_mul_f32_e32 v83, v83, v232
	v_mul_f32_e32 v84, v84, v232
	v_mul_f32_e32 v85, v85, v232
	v_mul_f32_e32 v86, v86, v232
	v_mul_f32_e32 v87, v87, v232
	v_mul_f32_e32 v88, v88, v232
	v_mul_f32_e32 v89, v89, v232
	v_mul_f32_e32 v66, v66, v232
	v_mul_f32_e32 v67, v67, v232
	v_mul_f32_e32 v68, v68, v232
	v_mul_f32_e32 v69, v69, v232
	v_mul_f32_e32 v70, v70, v232
	v_mul_f32_e32 v71, v71, v232
	v_mul_f32_e32 v72, v72, v232
	v_mul_f32_e32 v73, v73, v232
	v_mul_f32_e32 v50, v50, v232
	v_mul_f32_e32 v51, v51, v232
	v_mul_f32_e32 v52, v52, v232
	v_mul_f32_e32 v53, v53, v232
	v_mul_f32_e32 v54, v54, v232
	v_mul_f32_e32 v55, v55, v232
	v_mul_f32_e32 v56, v56, v232
	v_mul_f32_e32 v57, v57, v232
	v_mul_f32_e32 v34, v34, v232
	v_mul_f32_e32 v35, v35, v232
	v_mul_f32_e32 v36, v36, v232
	v_mul_f32_e32 v37, v37, v232
	v_mul_f32_e32 v38, v38, v232
	v_mul_f32_e32 v39, v39, v232
	v_mul_f32_e32 v40, v40, v232
	v_mul_f32_e32 v41, v41, v232
	v_mul_f32_e32 v18, v18, v232
	v_mul_f32_e32 v19, v19, v232
	v_mul_f32_e32 v20, v20, v232
	v_mul_f32_e32 v21, v21, v232
	v_mul_f32_e32 v22, v22, v232
	v_mul_f32_e32 v23, v23, v232
	v_mul_f32_e32 v24, v24, v232
	v_mul_f32_e32 v25, v25, v232
	v_mul_f32_e32 v2, v2, v232
	v_mul_f32_e32 v3, v3, v232
	v_mul_f32_e32 v4, v4, v232
	v_mul_f32_e32 v5, v5, v232
	v_mul_f32_e32 v6, v6, v232
	v_mul_f32_e32 v7, v7, v232
	v_mul_f32_e32 v8, v8, v232
	v_mul_f32_e32 v9, v9, v232
	v_mul_f32_e32 v122, v122, v244
	v_mul_f32_e32 v123, v123, v244
	v_mul_f32_e32 v124, v124, v244
	v_mul_f32_e32 v125, v125, v244
	v_mul_f32_e32 v126, v126, v244
	v_mul_f32_e32 v127, v127, v244
	v_mul_f32_e32 v128, v128, v244
	v_mul_f32_e32 v129, v129, v244
	v_mul_f32_e32 v106, v106, v244
	v_mul_f32_e32 v107, v107, v244
	v_mul_f32_e32 v108, v108, v244
	v_mul_f32_e32 v109, v109, v244
	v_mul_f32_e32 v110, v110, v244
	v_mul_f32_e32 v111, v111, v244
	v_mul_f32_e32 v112, v112, v244
	v_mul_f32_e32 v113, v113, v244
	v_mul_f32_e32 v90, v90, v244
	v_mul_f32_e32 v91, v91, v244
	v_mul_f32_e32 v92, v92, v244
	v_mul_f32_e32 v93, v93, v244
	v_mul_f32_e32 v94, v94, v244
	v_mul_f32_e32 v95, v95, v244
	v_mul_f32_e32 v96, v96, v244
	v_mul_f32_e32 v97, v97, v244
	v_mul_f32_e32 v74, v74, v244
	v_mul_f32_e32 v75, v75, v244
	v_mul_f32_e32 v76, v76, v244
	v_mul_f32_e32 v77, v77, v244
	v_mul_f32_e32 v78, v78, v244
	v_mul_f32_e32 v79, v79, v244
	v_mul_f32_e32 v80, v80, v244
	v_mul_f32_e32 v81, v81, v244
	v_mul_f32_e32 v58, v58, v244
	v_mul_f32_e32 v59, v59, v244
	v_mul_f32_e32 v60, v60, v244
	v_mul_f32_e32 v61, v61, v244
	v_mul_f32_e32 v62, v62, v244
	v_mul_f32_e32 v63, v63, v244
	v_mul_f32_e32 v64, v64, v244
	v_mul_f32_e32 v65, v65, v244
	v_mul_f32_e32 v42, v42, v244
	v_mul_f32_e32 v43, v43, v244
	v_mul_f32_e32 v44, v44, v244
	v_mul_f32_e32 v45, v45, v244
	v_mul_f32_e32 v46, v46, v244
	v_mul_f32_e32 v47, v47, v244
	v_mul_f32_e32 v48, v48, v244
	v_mul_f32_e32 v49, v49, v244
	v_mul_f32_e32 v26, v26, v244
	v_mul_f32_e32 v27, v27, v244
	v_mul_f32_e32 v28, v28, v244
	v_mul_f32_e32 v29, v29, v244
	v_mul_f32_e32 v30, v30, v244
	v_mul_f32_e32 v31, v31, v244
	v_mul_f32_e32 v32, v32, v244
	v_mul_f32_e32 v33, v33, v244
	v_mul_f32_e32 v10, v10, v244
	v_mul_f32_e32 v11, v11, v244
	v_mul_f32_e32 v12, v12, v244
	v_mul_f32_e32 v13, v13, v244
	v_mul_f32_e32 v14, v14, v244
	v_mul_f32_e32 v15, v15, v244
	v_mul_f32_e32 v16, v16, v244
	v_mul_f32_e32 v17, v17, v244
	s_cmp_lg_u64 s[0:1], 0
	s_cbranch_scc1 .Lat_ep_k
	v_mul_f32_e32 v114, v114, v210
	v_mul_f32_e32 v115, v115, v210
	v_mul_f32_e32 v116, v116, v210
	v_mul_f32_e32 v117, v117, v210
	v_mul_f32_e32 v118, v118, v210
	v_mul_f32_e32 v119, v119, v210
	v_mul_f32_e32 v120, v120, v210
	v_mul_f32_e32 v121, v121, v210
	v_mul_f32_e32 v98, v98, v210
	v_mul_f32_e32 v99, v99, v210
	v_mul_f32_e32 v100, v100, v210
	v_mul_f32_e32 v101, v101, v210
	v_mul_f32_e32 v102, v102, v210
	v_mul_f32_e32 v103, v103, v210
	v_mul_f32_e32 v104, v104, v210
	v_mul_f32_e32 v105, v105, v210
	v_mul_f32_e32 v82, v82, v210
	v_mul_f32_e32 v83, v83, v210
	v_mul_f32_e32 v84, v84, v210
	v_mul_f32_e32 v85, v85, v210
	v_mul_f32_e32 v86, v86, v210
	v_mul_f32_e32 v87, v87, v210
	v_mul_f32_e32 v88, v88, v210
	v_mul_f32_e32 v89, v89, v210
	v_mul_f32_e32 v66, v66, v210
	v_mul_f32_e32 v67, v67, v210
	v_mul_f32_e32 v68, v68, v210
	v_mul_f32_e32 v69, v69, v210
	v_mul_f32_e32 v70, v70, v210
	v_mul_f32_e32 v71, v71, v210
	v_mul_f32_e32 v72, v72, v210
	v_mul_f32_e32 v73, v73, v210
	v_mul_f32_e32 v50, v50, v210
	v_mul_f32_e32 v51, v51, v210
	v_mul_f32_e32 v52, v52, v210
	v_mul_f32_e32 v53, v53, v210
	v_mul_f32_e32 v54, v54, v210
	v_mul_f32_e32 v55, v55, v210
	v_mul_f32_e32 v56, v56, v210
	v_mul_f32_e32 v57, v57, v210
	v_mul_f32_e32 v34, v34, v210
	v_mul_f32_e32 v35, v35, v210
	v_mul_f32_e32 v36, v36, v210
	v_mul_f32_e32 v37, v37, v210
	v_mul_f32_e32 v38, v38, v210
	v_mul_f32_e32 v39, v39, v210
	v_mul_f32_e32 v40, v40, v210
	v_mul_f32_e32 v41, v41, v210
	v_mul_f32_e32 v18, v18, v210
	v_mul_f32_e32 v19, v19, v210
	v_mul_f32_e32 v20, v20, v210
	v_mul_f32_e32 v21, v21, v210
	v_mul_f32_e32 v22, v22, v210
	v_mul_f32_e32 v23, v23, v210
	v_mul_f32_e32 v24, v24, v210
	v_mul_f32_e32 v25, v25, v210
	v_mul_f32_e32 v2, v2, v210
	v_mul_f32_e32 v3, v3, v210
	v_mul_f32_e32 v4, v4, v210
	v_mul_f32_e32 v5, v5, v210
	v_mul_f32_e32 v6, v6, v210
	v_mul_f32_e32 v7, v7, v210
	v_mul_f32_e32 v8, v8, v210
	v_mul_f32_e32 v9, v9, v210
	v_mul_f32_e32 v122, v122, v210
	v_mul_f32_e32 v123, v123, v210
	v_mul_f32_e32 v124, v124, v210
	v_mul_f32_e32 v125, v125, v210
	v_mul_f32_e32 v126, v126, v210
	v_mul_f32_e32 v127, v127, v210
	v_mul_f32_e32 v128, v128, v210
	v_mul_f32_e32 v129, v129, v210
	v_mul_f32_e32 v106, v106, v210
	v_mul_f32_e32 v107, v107, v210
	v_mul_f32_e32 v108, v108, v210
	v_mul_f32_e32 v109, v109, v210
	v_mul_f32_e32 v110, v110, v210
	v_mul_f32_e32 v111, v111, v210
	v_mul_f32_e32 v112, v112, v210
	v_mul_f32_e32 v113, v113, v210
	v_mul_f32_e32 v90, v90, v210
	v_mul_f32_e32 v91, v91, v210
	v_mul_f32_e32 v92, v92, v210
	v_mul_f32_e32 v93, v93, v210
	v_mul_f32_e32 v94, v94, v210
	v_mul_f32_e32 v95, v95, v210
	v_mul_f32_e32 v96, v96, v210
	v_mul_f32_e32 v97, v97, v210
	v_mul_f32_e32 v74, v74, v210
	v_mul_f32_e32 v75, v75, v210
	v_mul_f32_e32 v76, v76, v210
	v_mul_f32_e32 v77, v77, v210
	v_mul_f32_e32 v78, v78, v210
	v_mul_f32_e32 v79, v79, v210
	v_mul_f32_e32 v80, v80, v210
	v_mul_f32_e32 v81, v81, v210
	v_mul_f32_e32 v58, v58, v210
	v_mul_f32_e32 v59, v59, v210
	v_mul_f32_e32 v60, v60, v210
	v_mul_f32_e32 v61, v61, v210
	v_mul_f32_e32 v62, v62, v210
	v_mul_f32_e32 v63, v63, v210
	v_mul_f32_e32 v64, v64, v210
	v_mul_f32_e32 v65, v65, v210
	v_mul_f32_e32 v42, v42, v210
	v_mul_f32_e32 v43, v43, v210
	v_mul_f32_e32 v44, v44, v210
	v_mul_f32_e32 v45, v45, v210
	v_mul_f32_e32 v46, v46, v210
	v_mul_f32_e32 v47, v47, v210
	v_mul_f32_e32 v48, v48, v210
	v_mul_f32_e32 v49, v49, v210
	v_mul_f32_e32 v26, v26, v210
	v_mul_f32_e32 v27, v27, v210
	v_mul_f32_e32 v28, v28, v210
	v_mul_f32_e32 v29, v29, v210
	v_mul_f32_e32 v30, v30, v210
	v_mul_f32_e32 v31, v31, v210
	v_mul_f32_e32 v32, v32, v210
	v_mul_f32_e32 v33, v33, v210
	v_mul_f32_e32 v10, v10, v210
	v_mul_f32_e32 v11, v11, v210
	v_mul_f32_e32 v12, v12, v210
	v_mul_f32_e32 v13, v13, v210
	v_mul_f32_e32 v14, v14, v210
	v_mul_f32_e32 v15, v15, v210
	v_mul_f32_e32 v16, v16, v210
	v_mul_f32_e32 v17, v17, v210
	v_lshl_add_u32 v250, v211, 4, s95
	ds_write_b128 v250, v[114:117]
	ds_write_b128 v250, v[118:121] offset:1024
	ds_write_b128 v250, v[98:101] offset:2048
	ds_write_b128 v250, v[102:105] offset:3072
	ds_write_b128 v250, v[82:85] offset:4096
	ds_write_b128 v250, v[86:89] offset:5120
	ds_write_b128 v250, v[66:69] offset:6144
	ds_write_b128 v250, v[70:73] offset:7168
	ds_write_b128 v250, v[50:53] offset:8192
	ds_write_b128 v250, v[54:57] offset:9216
	ds_write_b128 v250, v[34:37] offset:10240
	ds_write_b128 v250, v[38:41] offset:11264
	ds_write_b128 v250, v[18:21] offset:12288
	ds_write_b128 v250, v[22:25] offset:13312
	ds_write_b128 v250, v[2:5] offset:14336
	ds_write_b128 v250, v[6:9] offset:15360
	ds_write_b128 v250, v[122:125] offset:16384
	ds_write_b128 v250, v[126:129] offset:17408
	ds_write_b128 v250, v[106:109] offset:18432
	ds_write_b128 v250, v[110:113] offset:19456
	ds_write_b128 v250, v[90:93] offset:20480
	ds_write_b128 v250, v[94:97] offset:21504
	ds_write_b128 v250, v[74:77] offset:22528
	ds_write_b128 v250, v[78:81] offset:23552
	ds_write_b128 v250, v[58:61] offset:24576
	ds_write_b128 v250, v[62:65] offset:25600
	ds_write_b128 v250, v[42:45] offset:26624
	ds_write_b128 v250, v[46:49] offset:27648
	ds_write_b128 v250, v[26:29] offset:28672
	ds_write_b128 v250, v[30:33] offset:29696
	ds_write_b128 v250, v[10:13] offset:30720
	ds_write_b128 v250, v[14:17] offset:31744
	s_waitcnt lgkmcnt(0)
	s_barrier
	s_branch .Lat_ep_fin

	.amdhsa_kernel _Z10hybrid_fwd4Args
		.amdhsa_group_segment_fixed_size 0
		.amdhsa_private_segment_fixed_size 0
		.amdhsa_kernarg_size 376
		.amdhsa_user_sgpr_count 2
		.amdhsa_user_sgpr_dispatch_ptr 0
		.amdhsa_user_sgpr_queue_ptr 0
		.amdhsa_user_sgpr_kernarg_segment_ptr 1
		.amdhsa_user_sgpr_dispatch_id 0
		.amdhsa_user_sgpr_kernarg_preload_length 0
		.amdhsa_user_sgpr_kernarg_preload_offset 0
		.amdhsa_user_sgpr_private_segment_size 0
		.amdhsa_uses_dynamic_stack 0
		.amdhsa_enable_private_segment 0
		.amdhsa_system_sgpr_workgroup_id_x 1
		.amdhsa_system_sgpr_workgroup_id_y 0
		.amdhsa_system_sgpr_workgroup_id_z 0
		.amdhsa_system_sgpr_workgroup_info 0
		.amdhsa_system_vgpr_workitem_id 0
		.amdhsa_next_free_vgpr 255
		.amdhsa_next_free_sgpr 100
		.amdhsa_accum_offset 256
		.amdhsa_reserve_vcc 1
		.amdhsa_float_round_mode_32 0
		.amdhsa_float_round_mode_16_64 0
		.amdhsa_float_denorm_mode_32 3
		.amdhsa_float_denorm_mode_16_64 3
		.amdhsa_dx10_clamp 1
		.amdhsa_ieee_mode 1
		.amdhsa_fp16_overflow 0
		.amdhsa_tg_split 0
		.amdhsa_exception_fp_ieee_invalid_op 0
		.amdhsa_exception_fp_denorm_src 0
		.amdhsa_exception_fp_ieee_div_zero 0
		.amdhsa_exception_fp_ieee_overflow 0
		.amdhsa_exception_fp_ieee_underflow 0
		.amdhsa_exception_fp_ieee_inexact 0
		.amdhsa_exception_int_div_zero 0
	.end_amdhsa_kernel

amdhsa.kernels:
  - .agpr_count:     0
    .args:
      - .offset:         0
        .size:           120
        .value_kind:     by_value
      - .offset:         120
        .size:           4
        .value_kind:     hidden_block_count_x
      - .offset:         124
        .size:           4
        .value_kind:     hidden_block_count_y
      - .offset:         128
        .size:           4
        .value_kind:     hidden_block_count_z
      - .offset:         132
        .size:           2
        .value_kind:     hidden_group_size_x
      - .offset:         134
        .size:           2
        .value_kind:     hidden_group_size_y
      - .offset:         136
        .size:           2
        .value_kind:     hidden_group_size_z
      - .offset:         138
        .size:           2
        .value_kind:     hidden_remainder_x
      - .offset:         140
        .size:           2
        .value_kind:     hidden_remainder_y
      - .offset:         142
        .size:           2
        .value_kind:     hidden_remainder_z
      - .offset:         160
        .size:           8
        .value_kind:     hidden_global_offset_x
      - .offset:         168
        .size:           8
        .value_kind:     hidden_global_offset_y
      - .offset:         176
        .size:           8
        .value_kind:     hidden_global_offset_z
      - .offset:         184
        .size:           2
        .value_kind:     hidden_grid_dims
      - .offset:         240
        .size:           4
        .value_kind:     hidden_dynamic_lds_size
    .group_segment_fixed_size: 0
    .kernarg_segment_align: 8
    .kernarg_segment_size: 376
    .language:       OpenCL C
    .language_version:
      - 2
      - 0
    .max_flat_workgroup_size: 512
    .name:           _Z10hybrid_fwd4Args
    .private_segment_fixed_size: 0
    .sgpr_count:     106
    .sgpr_spill_count: 46
    .symbol:         _Z10hybrid_fwd4Args.kd
    .uniform_work_group_size: 1
    .uses_dynamic_stack: false
    .vgpr_count:     255
    .vgpr_spill_count: 0
    .wavefront_size: 64
